# v26 + removed nt cache hint from the 16 P4/P7 output stores
# speedup vs baseline: 1.0089x; 1.0047x over previous
; __device__ __forceinline__ void rms_store_bf16(const f32x4 (&v)[4], const float* g, bf16_t* orow, int lane) {
;     float s = 0.f;
; #pragma unroll
;     for (int j = 0; j < 4; ++j) s += (v[j].x * v[j].x + v[j].y * v[j].y) + (v[j].z * v[j].z + v[j].w * v[j].w);
;     const float rs = 1.f / sqrtf(wave_sum(s) * (1.f / 1024.f) + EPS);
; __global__ void __launch_bounds__(NTHR, 2) hymba_fwd(Params P) {
;     ...
;             for (int u = 0; u < 2; ++u) { const int t = t0 + u * NGW; tt[u] = t; const int tc = t < TT ? t : TT - 1;
;                 const int b = tc / LL, p = tc - b * LL;
;                 const float* src = (p < NMETA) ? P.meta + (size_t)p * 1024 : P.x + ((size_t)b * SEQ + p - NMETA) * 1024;
; #pragma unroll
;                 for (int j = 0; j < 4; ++j) { const u32x2 mq = __builtin_nontemporal_load((const u32x2*)(MIX + (size_t)tc * 1024) + lane + 64 * j);
;                     m[u][j] = (f32x4){bflo(mq.x), bfhi(mq.x), bflo(mq.y), bfhi(mq.y)}; xv[u][j] = __builtin_nontemporal_load((const f32x4*)src + lane + 64 * j); } }
; #pragma unroll
;             for (int u = 0; u < 2; ++u) { const int t = tt[u]; if (t >= TT) continue;
;                 float s = 0.f; f32x4 hv[4];
; #pragma unroll
;                 for (int j = 0; j < 4; ++j) s += (m[u][j].x * m[u][j].x + m[u][j].y * m[u][j].y) + (m[u][j].z * m[u][j].z + m[u][j].w * m[u][j].w);
;                 const float rs = 1.f / sqrtf(wave_sum(s) * (1.f / 1024.f) + EPS);
; #pragma unroll
;                 for (int j = 0; j < 4; ++j) { const f32x4 gg = *((const f32x4*)P.mix_post_g + lane + 64 * j);
;                     hv[j] = xv[u][j] + m[u][j] * rs * gg; u32x2 hq; hq.x = pk2(hv[j].x, hv[j].y); hq.y = pk2(hv[j].z, hv[j].w); __builtin_nontemporal_store(hq, (u32x2*)(H1 + (size_t)t * 1024) + lane + 64 * j); }
;                 rms_store_bf16(hv, P.ffn_pre_g, XN + (size_t)t * 1024, lane);
.LBB0_806:
	s_waitcnt vmcnt(5)
	v_and_b32_e32 v63, 0xffff0000, v6
	v_and_b32_e32 v65, 0xffff0000, v7
	v_lshlrev_b32_e32 v62, 16, v6
	v_lshlrev_b32_e32 v64, 16, v7
	s_waitcnt vmcnt(4)
	v_lshlrev_b32_e32 v66, 16, v4
	v_and_b32_e32 v69, 0xffff0000, v5
	v_and_b32_e32 v68, 0xffff0000, v4
	s_waitcnt vmcnt(2)
	v_lshlrev_b32_e32 v75, 16, v0
	v_and_b32_e32 v77, 0xffff0000, v0
	v_mul_f32_e32 v0, v65, v65
	v_mul_f32_e32 v4, v63, v63
	v_lshlrev_b32_e32 v67, 16, v5
	v_lshlrev_b32_e32 v70, 16, v2
	v_and_b32_e32 v71, 0xffff0000, v2
	v_lshlrev_b32_e32 v72, 16, v3
	v_and_b32_e32 v73, 0xffff0000, v3
	v_lshlrev_b32_e32 v78, 16, v1
	v_and_b32_e32 v79, 0xffff0000, v1
	v_pk_fma_f32 v[0:1], v[64:65], v[64:65], v[0:1] op_sel_hi:[1,1,0]
	v_pk_mul_f32 v[2:3], v[68:69], v[68:69]
	v_pk_fma_f32 v[4:5], v[62:63], v[62:63], v[4:5] op_sel_hi:[1,1,0]
	v_pk_fma_f32 v[2:3], v[66:67], v[66:67], v[2:3]
	v_mov_b32_e32 v74, v4
	v_mov_b32_e32 v6, v0
	v_mov_b32_e32 v7, v75
	v_mul_f32_e32 v8, v77, v77
	v_pk_add_f32 v[0:1], v[4:5], v[0:1]
	v_pk_mul_f32 v[4:5], v[74:75], v[6:7]
	v_pk_add_f32 v[2:3], v[2:3], v[2:3] op_sel:[0,1] op_sel_hi:[1,0]
	v_mov_b32_e32 v1, v5
	v_mov_b32_e32 v3, v8
	v_pk_add_f32 v[0:1], v[0:1], v[2:3]
	v_mul_f32_e32 v2, v71, v71
	v_mul_f32_e32 v4, v73, v73
	v_mul_f32_e32 v9, v78, v78
	v_mul_f32_e32 v10, v79, v79
	v_pk_fma_f32 v[2:3], v[70:71], v[70:71], v[2:3] op_sel_hi:[1,1,0]
	v_pk_fma_f32 v[4:5], v[72:73], v[72:73], v[4:5] op_sel_hi:[1,1,0]
	v_mov_b32_e32 v3, v9
	v_mov_b32_e32 v5, v10
	v_pk_add_f32 v[2:3], v[2:3], v[4:5]
	s_ashr_i32 s5, s4, 31
	v_pk_add_f32 v[0:1], v[0:1], v[2:3]
	s_lshl_b64 s[4:5], s[4:5], 11
	v_add_f32_e32 v0, v0, v1
	ds_bpermute_b32 v1, v50, v0
	v_lshl_add_u64 v[80:81], v[32:33], 0, s[4:5]
	v_lshl_add_u64 v[82:83], v[152:153], 4, s[14:15]
	global_load_dwordx4 v[12:15], v[82:83], off nt
	global_load_dwordx4 v[4:7], v[82:83], off offset:1024 nt
	s_cmp_gt_i32 s8, 0x807f
	s_waitcnt lgkmcnt(0)
	v_add_f32_e32 v0, v0, v1
	ds_bpermute_b32 v1, v51, v0
	s_waitcnt lgkmcnt(0)
	v_add_f32_e32 v0, v0, v1
	ds_bpermute_b32 v1, v52, v0
	s_waitcnt lgkmcnt(0)
	v_add_f32_e32 v0, v0, v1
	ds_bpermute_b32 v1, v53, v0
	s_waitcnt lgkmcnt(0)
	v_add_f32_e32 v0, v0, v1
	ds_bpermute_b32 v1, v54, v0
	s_waitcnt lgkmcnt(0)
	v_add_f32_e32 v0, v0, v1
	ds_bpermute_b32 v1, v55, v0
	s_waitcnt lgkmcnt(0)
	v_add_f32_e32 v0, v0, v1
	v_fmamk_f32 v0, v0, 0x3a800000, v56
	v_mul_f32_e32 v1, 0x4f800000, v0
	v_cmp_gt_f32_e32 vcc, s21, v0
	s_nop 1
	v_cndmask_b32_e32 v0, v0, v1, vcc
	v_sqrt_f32_e32 v1, v0
	s_nop 0
	v_add_u32_e32 v2, -1, v1
	v_fma_f32 v3, -v2, v1, v0
	v_cmp_ge_f32_e64 s[4:5], 0, v3
	v_add_u32_e32 v3, 1, v1
	s_nop 0
	v_cndmask_b32_e64 v2, v1, v2, s[4:5]
	v_fma_f32 v1, -v3, v1, v0
	v_cmp_lt_f32_e64 s[4:5], 0, v1
	s_nop 1
	v_cndmask_b32_e64 v1, v2, v3, s[4:5]
	v_mul_f32_e32 v2, 0x37800000, v1
	v_cndmask_b32_e32 v1, v1, v2, vcc
	v_cmp_class_f32_e32 vcc, v0, v57
	s_nop 1
	v_cndmask_b32_e32 v74, v1, v0, vcc
	v_div_scale_f32 v76, s[4:5], v74, v74, 1.0
	v_rcp_f32_e32 v84, v76
	global_load_dwordx2 v[46:47], v[80:81], off nt
	global_load_dwordx2 v[44:45], v[80:81], off offset:512 nt
	global_load_dwordx2 v[42:43], v[80:81], off offset:1024 nt
	global_load_dwordx2 v[48:49], v[80:81], off offset:1536 nt
	global_load_dwordx4 v[8:11], v[82:83], off offset:2048 nt
	global_load_dwordx4 v[0:3], v[82:83], off offset:3072 nt
	v_fma_f32 v80, -v76, v84, 1.0
	v_fmac_f32_e32 v84, v80, v84
	v_div_scale_f32 v80, vcc, 1.0, v74, 1.0
	v_mul_f32_e32 v81, v80, v84
	v_fma_f32 v82, -v76, v81, v80
	v_fmac_f32_e32 v81, v82, v84
	v_fma_f32 v76, -v76, v81, v80
	v_div_fmas_f32 v76, v76, v84, v81
	v_div_fixup_f32 v74, v76, v74, 1.0
	v_pk_mul_f32 v[62:63], v[74:75], v[62:63] op_sel_hi:[0,1]
	v_pk_mul_f32 v[64:65], v[74:75], v[64:65] op_sel_hi:[0,1]
	s_waitcnt vmcnt(8)
	v_pk_fma_f32 v[60:61], v[98:99], v[64:65], v[30:31]
	v_pk_fma_f32 v[58:59], v[96:97], v[62:63], v[28:29]
	v_lshl_add_u64 v[80:81], v[36:37], 0, s[12:13]
	v_cvt_pk_bf16_f32 v28, v58, v59
	v_cvt_pk_bf16_f32 v29, v60, v61
	global_store_dwordx2 v[80:81], v[28:29], off
	v_mov_b32_e32 v62, v66
	v_mov_b32_e32 v63, v68
	v_mov_b32_e32 v68, v67
	v_pk_mul_f32 v[62:63], v[74:75], v[62:63] op_sel_hi:[0,1]
	v_pk_mul_f32 v[64:65], v[74:75], v[68:69] op_sel_hi:[0,1]
	v_mov_b32_e32 v76, v75
	v_pk_mul_f32 v[66:67], v[60:61], v[60:61]
	v_pk_mul_f32 v[68:69], v[58:59], v[58:59]
	v_pk_fma_f32 v[30:31], v[102:103], v[64:65], v[26:27]
	v_pk_fma_f32 v[28:29], v[100:101], v[62:63], v[24:25]
	v_cvt_pk_bf16_f32 v25, v30, v31
	v_cvt_pk_bf16_f32 v24, v28, v29
	global_store_dwordx2 v[80:81], v[24:25], off offset:512
	v_pk_mul_f32 v[62:63], v[74:75], v[70:71] op_sel_hi:[0,1]
	v_pk_mul_f32 v[64:65], v[74:75], v[72:73] op_sel_hi:[0,1]
	v_pk_mov_b32 v[70:71], v[68:69], v[66:67] op_sel:[1,0]
	v_mov_b32_e32 v69, v67
	v_pk_add_f32 v[66:67], v[70:71], v[68:69]
	v_pk_mul_f32 v[68:69], v[28:29], v[28:29]
	v_pk_mul_f32 v[70:71], v[30:31], v[30:31]
	v_pk_add_f32 v[66:67], v[66:67], v[66:67] op_sel_hi:[0,1]
	v_pk_mov_b32 v[72:73], v[68:69], v[70:71] op_sel:[1,0]
	v_mov_b32_e32 v69, v71
	v_pk_add_f32 v[68:69], v[72:73], v[68:69]
	v_pk_fma_f32 v[26:27], v[106:107], v[64:65], v[22:23]
	v_pk_fma_f32 v[24:25], v[104:105], v[62:63], v[20:21]
	v_cvt_pk_bf16_f32 v21, v26, v27
	v_cvt_pk_bf16_f32 v20, v24, v25
	global_store_dwordx2 v[80:81], v[20:21], off offset:1024
	v_pk_mul_f32 v[62:63], v[74:75], v[76:77] op_sel_hi:[0,1]
	v_pk_mul_f32 v[64:65], v[74:75], v[78:79] op_sel_hi:[0,1]
	v_pk_add_f32 v[68:69], v[68:69], v[68:69] op_sel_hi:[0,1]
	v_mul_f32_e32 v66, v24, v24
	v_mul_f32_e32 v68, v26, v26
	v_pk_fma_f32 v[70:71], v[24:25], v[24:25], v[66:67] op_sel_hi:[1,1,0]
	v_pk_fma_f32 v[72:73], v[26:27], v[26:27], v[68:69] op_sel_hi:[1,1,0]
	v_pk_fma_f32 v[22:23], v[110:111], v[64:65], v[18:19]
	v_pk_fma_f32 v[20:21], v[108:109], v[62:63], v[16:17]
	v_cvt_pk_bf16_f32 v17, v22, v23
	v_cvt_pk_bf16_f32 v16, v20, v21
	global_store_dwordx2 v[80:81], v[16:17], off offset:1536
	v_mul_f32_e32 v70, v20, v20
	v_mul_f32_e32 v72, v21, v21
	v_mul_f32_e32 v66, v22, v22
	v_mul_f32_e32 v68, v23, v23
	v_pk_add_f32 v[62:63], v[70:71], v[72:73]
	v_pk_add_f32 v[64:65], v[66:67], v[68:69]
	s_nop 0
	v_pk_add_f32 v[62:63], v[62:63], v[64:65]
	s_nop 0
	v_add_f32_e32 v62, v62, v63
	ds_bpermute_b32 v63, v50, v62
	s_waitcnt lgkmcnt(0)
; __device__ __forceinline__ void rms_store_bf16(const f32x4 (&v)[4], const float* g, bf16_t* orow, int lane) {
;     float s = 0.f;
; #pragma unroll
;     for (int j = 0; j < 4; ++j) s += (v[j].x * v[j].x + v[j].y * v[j].y) + (v[j].z * v[j].z + v[j].w * v[j].w);
;     const float rs = 1.f / sqrtf(wave_sum(s) * (1.f / 1024.f) + EPS);
;     unsigned long long* o8 = (unsigned long long*)orow + lane;
; #pragma unroll
;     for (int j = 0; j < 4; ++j) { const f32x4 gg = *((const f32x4*)g + lane + 64 * j);
;         o8[64 * j] = (unsigned long long)pk2(v[j].x * rs * gg.x, v[j].y * rs * gg.y) | ((unsigned long long)pk2(v[j].z * rs * gg.z, v[j].w * rs * gg.w) << 32); }
; __global__ void __launch_bounds__(NTHR, 2) hymba_fwd(Params P) {
;     ...
;             for (int u = 0; u < 2; ++u) { const int t = tt[u]; if (t >= TT) continue;
;                 float s = 0.f; f32x4 hv[4];
; #pragma unroll
;                 for (int j = 0; j < 4; ++j) s += (m[u][j].x * m[u][j].x + m[u][j].y * m[u][j].y) + (m[u][j].z * m[u][j].z + m[u][j].w * m[u][j].w);
;                 const float rs = 1.f / sqrtf(wave_sum(s) * (1.f / 1024.f) + EPS);
	v_add_f32_e32 v62, v62, v63
	ds_bpermute_b32 v63, v51, v62
	s_waitcnt lgkmcnt(0)
	v_add_f32_e32 v62, v62, v63
	ds_bpermute_b32 v63, v52, v62
	s_waitcnt lgkmcnt(0)
	v_add_f32_e32 v62, v62, v63
	ds_bpermute_b32 v63, v53, v62
	s_waitcnt lgkmcnt(0)
	v_add_f32_e32 v62, v62, v63
	ds_bpermute_b32 v63, v54, v62
	s_waitcnt lgkmcnt(0)
	v_add_f32_e32 v62, v62, v63
	ds_bpermute_b32 v63, v55, v62
	s_waitcnt lgkmcnt(0)
	v_add_f32_e32 v62, v62, v63
	v_fmamk_f32 v62, v62, 0x3a800000, v56
	v_mul_f32_e32 v63, 0x4f800000, v62
	v_cmp_gt_f32_e32 vcc, s21, v62
	s_nop 1
	v_cndmask_b32_e32 v62, v62, v63, vcc
	v_sqrt_f32_e32 v63, v62
	s_nop 0
	v_add_u32_e32 v64, -1, v63
	v_add_u32_e32 v65, 1, v63
	v_fma_f32 v66, -v64, v63, v62
	v_fma_f32 v67, -v65, v63, v62
	v_cmp_ge_f32_e64 s[4:5], 0, v66
	s_nop 1
	v_cndmask_b32_e64 v63, v63, v64, s[4:5]
	v_cmp_lt_f32_e64 s[4:5], 0, v67
	s_nop 1
	v_cndmask_b32_e64 v63, v63, v65, s[4:5]
	v_mul_f32_e32 v64, 0x37800000, v63
	v_cndmask_b32_e32 v63, v63, v64, vcc
	v_cmp_class_f32_e32 vcc, v62, v57
	s_nop 1
	v_cndmask_b32_e32 v64, v63, v62, vcc
	v_div_scale_f32 v65, s[4:5], v64, v64, 1.0
	v_rcp_f32_e32 v66, v65
	v_div_scale_f32 v67, vcc, 1.0, v64, 1.0
	v_lshl_add_u64 v[62:63], v[38:39], 0, s[12:13]
	v_fma_f32 v68, -v65, v66, 1.0
	v_fmac_f32_e32 v66, v68, v66
	v_mul_f32_e32 v68, v67, v66
	v_fma_f32 v69, -v65, v68, v67
	v_fmac_f32_e32 v68, v69, v66
	v_fma_f32 v65, -v65, v68, v67
	v_div_fmas_f32 v65, v65, v66, v68
	v_div_fixup_f32 v64, v65, v64, 1.0
	v_pk_mul_f32 v[58:59], v[58:59], v[64:65] op_sel_hi:[1,0]
	v_pk_mul_f32 v[60:61], v[60:61], v[64:65] op_sel_hi:[1,0]
	v_pk_mul_f32 v[16:17], v[112:113], v[58:59]
	v_pk_mul_f32 v[18:19], v[114:115], v[60:61]
	v_cvt_pk_bf16_f32 v16, v16, v17
	v_cvt_pk_bf16_f32 v17, v18, v19
	global_store_dwordx2 v[62:63], v[16:17], off
	v_pk_mul_f32 v[28:29], v[28:29], v[64:65] op_sel_hi:[1,0]
	v_pk_mul_f32 v[30:31], v[30:31], v[64:65] op_sel_hi:[1,0]
	v_pk_mul_f32 v[24:25], v[24:25], v[64:65] op_sel_hi:[1,0]
	v_pk_mul_f32 v[26:27], v[26:27], v[64:65] op_sel_hi:[1,0]
	v_pk_mul_f32 v[20:21], v[20:21], v[64:65] op_sel_hi:[1,0]
	v_pk_mul_f32 v[22:23], v[22:23], v[64:65] op_sel_hi:[1,0]
	v_pk_mul_f32 v[16:17], v[116:117], v[28:29]
	v_pk_mul_f32 v[18:19], v[118:119], v[30:31]
	v_cvt_pk_bf16_f32 v16, v16, v17
	v_cvt_pk_bf16_f32 v17, v18, v19
	global_store_dwordx2 v[62:63], v[16:17], off offset:512
	v_pk_mul_f32 v[16:17], v[120:121], v[24:25]
	v_pk_mul_f32 v[18:19], v[122:123], v[26:27]
	v_cvt_pk_bf16_f32 v16, v16, v17
	v_cvt_pk_bf16_f32 v17, v18, v19
	global_store_dwordx2 v[62:63], v[16:17], off offset:1024
	v_pk_mul_f32 v[16:17], v[20:21], v[124:125]
	v_pk_mul_f32 v[18:19], v[22:23], v[126:127]
	v_cvt_pk_bf16_f32 v16, v16, v17
	v_cvt_pk_bf16_f32 v17, v18, v19
	global_store_dwordx2 v[62:63], v[16:17], off offset:1536
	s_cbranch_scc1 .LBB0_797
	s_waitcnt vmcnt(8)
	v_and_b32_e32 v27, 0xffff0000, v46
	v_and_b32_e32 v29, 0xffff0000, v47
	v_lshlrev_b32_e32 v21, 16, v48
	v_lshlrev_b32_e32 v26, 16, v46
	v_lshlrev_b32_e32 v28, 16, v47
	v_mul_f32_e32 v16, v29, v29
	v_lshlrev_b32_e32 v31, 16, v45
	v_lshlrev_b32_e32 v30, 16, v44
	v_and_b32_e32 v45, 0xffff0000, v45
	v_and_b32_e32 v44, 0xffff0000, v44
	v_mul_f32_e32 v20, v27, v27
	v_and_b32_e32 v23, 0xffff0000, v48
	v_lshlrev_b32_e32 v24, 16, v49
	v_and_b32_e32 v25, 0xffff0000, v49
	v_pk_fma_f32 v[16:17], v[28:29], v[28:29], v[16:17] op_sel_hi:[1,1,0]
	v_pk_mul_f32 v[18:19], v[44:45], v[44:45]
	v_pk_fma_f32 v[48:49], v[26:27], v[26:27], v[20:21] op_sel_hi:[1,1,0]
	v_pk_fma_f32 v[18:19], v[30:31], v[30:31], v[18:19]
	v_mov_b32_e32 v20, v48
	v_mov_b32_e32 v58, v16
	v_mov_b32_e32 v59, v21
	v_mul_f32_e32 v22, v23, v23
	v_pk_add_f32 v[16:17], v[48:49], v[16:17]
	v_pk_mul_f32 v[48:49], v[20:21], v[58:59]
	v_pk_add_f32 v[18:19], v[18:19], v[18:19] op_sel:[0,1] op_sel_hi:[1,0]
	v_lshlrev_b32_e32 v46, 16, v42
	v_and_b32_e32 v47, 0xffff0000, v42
	v_lshlrev_b32_e32 v42, 16, v43
	v_and_b32_e32 v43, 0xffff0000, v43
	v_mov_b32_e32 v17, v49
	v_mov_b32_e32 v19, v22
	v_pk_add_f32 v[16:17], v[16:17], v[18:19]
	v_mul_f32_e32 v18, v47, v47
	v_mul_f32_e32 v20, v43, v43
	v_mul_f32_e32 v60, v24, v24
	v_mul_f32_e32 v61, v25, v25
	v_pk_fma_f32 v[18:19], v[46:47], v[46:47], v[18:19] op_sel_hi:[1,1,0]
	v_pk_fma_f32 v[48:49], v[42:43], v[42:43], v[20:21] op_sel_hi:[1,1,0]
	v_mov_b32_e32 v19, v60
	v_mov_b32_e32 v49, v61
	v_pk_add_f32 v[18:19], v[18:19], v[48:49]
	s_ashr_i32 s9, s8, 31
	v_pk_add_f32 v[48:49], v[16:17], v[18:19]
	v_add_f32_e32 v20, v48, v49
	ds_bpermute_b32 v22, v50, v20
	s_lshl_b64 s[8:9], s[8:9], 11
	s_waitcnt lgkmcnt(0)
	v_add_f32_e32 v20, v20, v22
	ds_bpermute_b32 v22, v51, v20
	s_waitcnt lgkmcnt(0)
	v_add_f32_e32 v20, v20, v22
	ds_bpermute_b32 v22, v52, v20
	s_waitcnt lgkmcnt(0)
	v_add_f32_e32 v20, v20, v22
	ds_bpermute_b32 v22, v53, v20
	s_waitcnt lgkmcnt(0)
	v_add_f32_e32 v20, v20, v22
	ds_bpermute_b32 v22, v54, v20
	s_waitcnt lgkmcnt(0)
	v_add_f32_e32 v20, v20, v22
	ds_bpermute_b32 v22, v55, v20
	s_waitcnt lgkmcnt(0)
; __device__ __forceinline__ void rms_store_bf16(const f32x4 (&v)[4], const float* g, bf16_t* orow, int lane) {
;     float s = 0.f;
; #pragma unroll
;     for (int j = 0; j < 4; ++j) s += (v[j].x * v[j].x + v[j].y * v[j].y) + (v[j].z * v[j].z + v[j].w * v[j].w);
;     const float rs = 1.f / sqrtf(wave_sum(s) * (1.f / 1024.f) + EPS);
;     unsigned long long* o8 = (unsigned long long*)orow + lane;
; #pragma unroll
;     for (int j = 0; j < 4; ++j) { const f32x4 gg = *((const f32x4*)g + lane + 64 * j);
;         o8[64 * j] = (unsigned long long)pk2(v[j].x * rs * gg.x, v[j].y * rs * gg.y) | ((unsigned long long)pk2(v[j].z * rs * gg.z, v[j].w * rs * gg.w) << 32); }
; __global__ void __launch_bounds__(NTHR, 2) hymba_fwd(Params P) {
;     ...
;                 const float rs = 1.f / sqrtf(wave_sum(s) * (1.f / 1024.f) + EPS);
; #pragma unroll
;                 for (int j = 0; j < 4; ++j) { const f32x4 gg = *((const f32x4*)P.mix_post_g + lane + 64 * j);
;                     hv[j] = xv[u][j] + m[u][j] * rs * gg; u32x2 hq; hq.x = pk2(hv[j].x, hv[j].y); hq.y = pk2(hv[j].z, hv[j].w); __builtin_nontemporal_store(hq, (u32x2*)(H1 + (size_t)t * 1024) + lane + 64 * j); }
;                 rms_store_bf16(hv, P.ffn_pre_g, XN + (size_t)t * 1024, lane);
	v_add_f32_e32 v20, v20, v22
	v_fmamk_f32 v20, v20, 0x3a800000, v56
	v_mul_f32_e32 v22, 0x4f800000, v20
	v_cmp_gt_f32_e32 vcc, s21, v20
	s_nop 1
	v_cndmask_b32_e32 v20, v20, v22, vcc
	v_sqrt_f32_e32 v22, v20
	s_nop 0
	v_add_u32_e32 v48, -1, v22
	v_fma_f32 v49, -v48, v22, v20
	v_cmp_ge_f32_e64 s[4:5], 0, v49
	v_add_u32_e32 v49, 1, v22
	s_nop 0
	v_cndmask_b32_e64 v48, v22, v48, s[4:5]
	v_fma_f32 v22, -v49, v22, v20
	v_cmp_lt_f32_e64 s[4:5], 0, v22
	s_nop 1
	v_cndmask_b32_e64 v22, v48, v49, s[4:5]
	v_mul_f32_e32 v48, 0x37800000, v22
	v_cndmask_b32_e32 v22, v22, v48, vcc
	v_cmp_class_f32_e32 vcc, v20, v57
	s_nop 1
	v_cndmask_b32_e32 v20, v22, v20, vcc
	v_div_scale_f32 v22, s[4:5], v20, v20, 1.0
	v_rcp_f32_e32 v48, v22
	s_nop 0
	v_fma_f32 v49, -v22, v48, 1.0
	v_fmac_f32_e32 v48, v49, v48
	v_div_scale_f32 v49, vcc, 1.0, v20, 1.0
	v_mul_f32_e32 v58, v49, v48
	v_fma_f32 v59, -v22, v58, v49
	v_fmac_f32_e32 v58, v59, v48
	v_fma_f32 v22, -v22, v58, v49
	v_div_fmas_f32 v22, v22, v48, v58
	v_div_fixup_f32 v20, v22, v20, 1.0
	v_pk_mul_f32 v[26:27], v[20:21], v[26:27] op_sel_hi:[0,1]
	v_pk_mul_f32 v[28:29], v[20:21], v[28:29] op_sel_hi:[0,1]
	v_pk_fma_f32 v[18:19], v[98:99], v[28:29], v[14:15]
	v_pk_fma_f32 v[16:17], v[96:97], v[26:27], v[12:13]
	v_lshl_add_u64 v[48:49], v[36:37], 0, s[8:9]
	v_cvt_pk_bf16_f32 v12, v16, v17
	v_cvt_pk_bf16_f32 v13, v18, v19
	global_store_dwordx2 v[48:49], v[12:13], off
	v_mov_b32_e32 v26, v30
	v_mov_b32_e32 v27, v44
	v_mov_b32_e32 v44, v31
	v_pk_mul_f32 v[26:27], v[20:21], v[26:27] op_sel_hi:[0,1]
	v_pk_mul_f32 v[28:29], v[20:21], v[44:45] op_sel_hi:[0,1]
	v_mov_b32_e32 v22, v21
	v_pk_mul_f32 v[22:23], v[20:21], v[22:23] op_sel_hi:[0,1]
	v_pk_fma_f32 v[14:15], v[102:103], v[28:29], v[6:7]
	v_pk_fma_f32 v[12:13], v[100:101], v[26:27], v[4:5]
	v_cvt_pk_bf16_f32 v5, v14, v15
	v_cvt_pk_bf16_f32 v4, v12, v13
	global_store_dwordx2 v[48:49], v[4:5], off offset:512
	v_pk_mul_f32 v[26:27], v[20:21], v[46:47] op_sel_hi:[0,1]
	v_pk_mul_f32 v[28:29], v[20:21], v[42:43] op_sel_hi:[0,1]
	v_pk_mul_f32 v[20:21], v[20:21], v[24:25] op_sel_hi:[0,1]
	v_pk_mul_f32 v[24:25], v[18:19], v[18:19]
	v_pk_fma_f32 v[10:11], v[106:107], v[28:29], v[10:11]
	v_pk_fma_f32 v[8:9], v[104:105], v[26:27], v[8:9]
	v_cvt_pk_bf16_f32 v5, v10, v11
	v_cvt_pk_bf16_f32 v4, v8, v9
	global_store_dwordx2 v[48:49], v[4:5], off offset:1024
	v_pk_mul_f32 v[26:27], v[16:17], v[16:17]
	v_pk_fma_f32 v[6:7], v[110:111], v[20:21], v[2:3]
	v_pk_fma_f32 v[4:5], v[108:109], v[22:23], v[0:1]
	v_cvt_pk_bf16_f32 v1, v6, v7
	v_cvt_pk_bf16_f32 v0, v4, v5
	global_store_dwordx2 v[48:49], v[0:1], off offset:1536
	v_pk_mov_b32 v[28:29], v[26:27], v[24:25] op_sel:[1,0]
	v_mov_b32_e32 v27, v25
	v_pk_add_f32 v[24:25], v[28:29], v[26:27]
	v_pk_mul_f32 v[26:27], v[12:13], v[12:13]
	v_pk_mul_f32 v[28:29], v[14:15], v[14:15]
	v_pk_add_f32 v[24:25], v[24:25], v[24:25] op_sel_hi:[0,1]
	v_pk_mov_b32 v[30:31], v[26:27], v[28:29] op_sel:[1,0]
	v_mov_b32_e32 v27, v29
	v_pk_add_f32 v[26:27], v[30:31], v[26:27]
	v_mul_f32_e32 v24, v8, v8
	v_pk_add_f32 v[26:27], v[26:27], v[26:27] op_sel_hi:[0,1]
	v_mul_f32_e32 v26, v10, v10
	v_pk_fma_f32 v[28:29], v[8:9], v[8:9], v[24:25] op_sel_hi:[1,1,0]
	v_pk_fma_f32 v[30:31], v[10:11], v[10:11], v[26:27] op_sel_hi:[1,1,0]
	v_mul_f32_e32 v28, v4, v4
	v_mul_f32_e32 v30, v5, v5
	v_mul_f32_e32 v24, v6, v6
	v_mul_f32_e32 v26, v7, v7
	v_pk_add_f32 v[20:21], v[28:29], v[30:31]
	v_pk_add_f32 v[22:23], v[24:25], v[26:27]
	s_nop 0
	v_pk_add_f32 v[20:21], v[20:21], v[22:23]
	s_nop 0
	v_add_f32_e32 v20, v20, v21
	ds_bpermute_b32 v21, v50, v20
	s_waitcnt lgkmcnt(0)
	v_add_f32_e32 v20, v20, v21
	ds_bpermute_b32 v21, v51, v20
	s_waitcnt lgkmcnt(0)
	v_add_f32_e32 v20, v20, v21
	ds_bpermute_b32 v21, v52, v20
	s_waitcnt lgkmcnt(0)
	v_add_f32_e32 v20, v20, v21
	ds_bpermute_b32 v21, v53, v20
	s_waitcnt lgkmcnt(0)
	v_add_f32_e32 v20, v20, v21
	ds_bpermute_b32 v21, v54, v20
	s_waitcnt lgkmcnt(0)
	v_add_f32_e32 v20, v20, v21
	ds_bpermute_b32 v21, v55, v20
	s_waitcnt lgkmcnt(0)
	v_add_f32_e32 v20, v20, v21
	v_fmamk_f32 v20, v20, 0x3a800000, v56
	v_mul_f32_e32 v21, 0x4f800000, v20
	v_cmp_gt_f32_e32 vcc, s21, v20
	s_nop 1
	v_cndmask_b32_e32 v20, v20, v21, vcc
	v_sqrt_f32_e32 v21, v20
	s_nop 0
	v_add_u32_e32 v22, -1, v21
	v_add_u32_e32 v23, 1, v21
	v_fma_f32 v24, -v22, v21, v20
	v_fma_f32 v25, -v23, v21, v20
	v_cmp_ge_f32_e64 s[4:5], 0, v24
	s_nop 1
	v_cndmask_b32_e64 v21, v21, v22, s[4:5]
	v_cmp_lt_f32_e64 s[4:5], 0, v25
	s_nop 1
	v_cndmask_b32_e64 v21, v21, v23, s[4:5]
	v_mul_f32_e32 v22, 0x37800000, v21
	v_cndmask_b32_e32 v21, v21, v22, vcc
	v_cmp_class_f32_e32 vcc, v20, v57
	s_nop 1
	v_cndmask_b32_e32 v22, v21, v20, vcc
	v_div_scale_f32 v23, s[4:5], v22, v22, 1.0
	v_rcp_f32_e32 v24, v23
	v_div_scale_f32 v25, vcc, 1.0, v22, 1.0
	v_lshl_add_u64 v[20:21], v[38:39], 0, s[8:9]
	v_fma_f32 v26, -v23, v24, 1.0
	v_fmac_f32_e32 v24, v26, v24
	v_mul_f32_e32 v26, v25, v24
	v_fma_f32 v27, -v23, v26, v25
	v_fmac_f32_e32 v26, v27, v24
	v_fma_f32 v23, -v23, v26, v25
	v_div_fmas_f32 v23, v23, v24, v26
	v_div_fixup_f32 v22, v23, v22, 1.0
	v_pk_mul_f32 v[16:17], v[16:17], v[22:23] op_sel_hi:[1,0]
	v_pk_mul_f32 v[18:19], v[18:19], v[22:23] op_sel_hi:[1,0]
	v_pk_mul_f32 v[0:1], v[112:113], v[16:17]
	v_pk_mul_f32 v[2:3], v[114:115], v[18:19]
	v_cvt_pk_bf16_f32 v0, v0, v1
	v_cvt_pk_bf16_f32 v1, v2, v3
	global_store_dwordx2 v[20:21], v[0:1], off
	v_pk_mul_f32 v[12:13], v[12:13], v[22:23] op_sel_hi:[1,0]
	v_pk_mul_f32 v[14:15], v[14:15], v[22:23] op_sel_hi:[1,0]
	v_pk_mul_f32 v[8:9], v[8:9], v[22:23] op_sel_hi:[1,0]
	v_pk_mul_f32 v[10:11], v[10:11], v[22:23] op_sel_hi:[1,0]
	v_pk_mul_f32 v[4:5], v[4:5], v[22:23] op_sel_hi:[1,0]
	v_pk_mul_f32 v[6:7], v[6:7], v[22:23] op_sel_hi:[1,0]
	v_pk_mul_f32 v[0:1], v[116:117], v[12:13]
	v_pk_mul_f32 v[2:3], v[118:119], v[14:15]
	v_cvt_pk_bf16_f32 v0, v0, v1
	v_cvt_pk_bf16_f32 v1, v2, v3
	global_store_dwordx2 v[20:21], v[0:1], off offset:512
	v_pk_mul_f32 v[0:1], v[120:121], v[8:9]
	v_pk_mul_f32 v[2:3], v[122:123], v[10:11]
	v_cvt_pk_bf16_f32 v0, v0, v1
	v_cvt_pk_bf16_f32 v1, v2, v3
	global_store_dwordx2 v[20:21], v[0:1], off offset:1024
	v_pk_mul_f32 v[0:1], v[4:5], v[124:125]
	v_pk_mul_f32 v[2:3], v[6:7], v[126:127]
	v_cvt_pk_bf16_f32 v0, v0, v1
	v_cvt_pk_bf16_f32 v1, v2, v3
	global_store_dwordx2 v[20:21], v[0:1], off offset:1536
	s_branch .LBB0_797

; __global__ void __launch_bounds__(NTHR, 2) hymba_fwd(Params P) {
;     ...
;         for (int t0 = gw; t0 < NB * SEQ; t0 += 2 * NGW) {
;             f32x4 f[2][4], hv[2][4];
; #pragma unroll
;             for (int u = 0; u < 2; ++u) { int tr = t0 + u * NGW; tr = tr < NB * SEQ ? tr : NB * SEQ - 1;
;                 const int b = tr / SEQ, s = tr - b * SEQ; const size_t t = (size_t)b * LL + NMETA + s;
; #pragma unroll
;                 for (int j = 0; j < 4; ++j) { const u32x2 fq2 = __builtin_nontemporal_load((const u32x2*)(FB + (size_t)tr * 1024) + lane + 64 * j);
;                     f[u][j] = (f32x4){bflo(fq2.x), bfhi(fq2.x), bflo(fq2.y), bfhi(fq2.y)}; const u32x2 hq = __builtin_nontemporal_load((const u32x2*)(H1 + t * 1024) + lane + 64 * j); hv[u][j] = (f32x4){bflo(hq.x), bfhi(hq.x), bflo(hq.y), bfhi(hq.y)}; } }
; #pragma unroll
;             for (int u = 0; u < 2; ++u) { const int tr = t0 + u * NGW; if (tr >= NB * SEQ) continue;
;                 float ss = 0.f;
; #pragma unroll
;                 for (int j = 0; j < 4; ++j) ss += (f[u][j].x * f[u][j].x + f[u][j].y * f[u][j].y) + (f[u][j].z * f[u][j].z + f[u][j].w * f[u][j].w);
;                 const float rs = 1.f / sqrtf(wave_sum(ss) * (1.f / 1024.f) + EPS);
.LBB0_1093:
	s_add_i32 s4, s89, s70
	s_min_i32 s6, s4, 0x7fff
	s_ashr_i32 s7, s6, 31
	s_lshr_b32 s0, s7, 20
	s_add_i32 s0, s6, s0
	s_ashr_i32 s1, s0, 12
	s_and_b32 s0, s0, 0xfffff000
	s_sub_i32 s0, s6, s0
	s_mul_hi_i32 s5, s1, 0x1010
	s_mulk_i32 s1, 0x1010
	s_ashr_i32 s11, s0, 31
	s_add_u32 s0, s1, s0
	s_addc_u32 s1, s5, s11
	s_ashr_i32 s71, s70, 31
	s_lshr_b32 s5, s71, 20
	s_add_i32 s5, s70, s5
	s_ashr_i32 s11, s5, 12
	s_and_b32 s5, s5, 0xfffff000
	s_sub_i32 s5, s70, s5
	s_lshl_b64 s[0:1], s[0:1], 11
	s_lshl_b64 s[6:7], s[6:7], 11
	s_mul_hi_i32 s13, s11, 0x1010
	s_mulk_i32 s11, 0x1010
	s_ashr_i32 s14, s5, 31
	s_add_u32 s12, s11, s5
	s_addc_u32 s13, s13, s14
	s_lshl_b64 s[14:15], s[70:71], 11
	v_lshl_add_u64 v[8:9], v[0:1], 0, s[14:15]
	s_lshl_b64 s[12:13], s[12:13], 11
	global_load_dwordx2 v[10:11], v[8:9], off offset:1536 nt
	global_load_dwordx2 v[12:13], v[8:9], off nt
	global_load_dwordx2 v[16:17], v[8:9], off offset:512 nt
	v_lshl_add_u64 v[14:15], v[2:3], 0, s[12:13]
	v_add_co_u32_e32 v18, vcc, s9, v14
	v_lshl_add_u64 v[56:57], v[14:15], 0, s[2:3]
	s_nop 0
	v_addc_co_u32_e32 v19, vcc, 0, v15, vcc
	global_load_dwordx2 v[36:37], v[18:19], off nt
	global_load_dwordx2 v[20:21], v[8:9], off offset:1024 nt
	s_waitcnt vmcnt(4)
	v_lshlrev_b32_e32 v39, 16, v10
	s_waitcnt vmcnt(3)
	v_and_b32_e32 v45, 0xffff0000, v12
	v_and_b32_e32 v47, 0xffff0000, v13
	v_mov_b32_e32 v9, v39
	v_lshlrev_b32_e32 v44, 16, v12
	v_lshlrev_b32_e32 v46, 16, v13
	s_waitcnt vmcnt(2)
	v_and_b32_e32 v51, 0xffff0000, v17
	v_and_b32_e32 v50, 0xffff0000, v16
	v_mul_f32_e32 v8, v47, v47
	v_mul_f32_e32 v12, v45, v45
	v_and_b32_e32 v41, 0xffff0000, v10
	v_lshlrev_b32_e32 v42, 16, v11
	v_and_b32_e32 v43, 0xffff0000, v11
	v_lshlrev_b32_e32 v49, 16, v17
	v_lshlrev_b32_e32 v48, 16, v16
	s_waitcnt vmcnt(0)
	v_lshlrev_b32_e32 v52, 16, v20
	v_and_b32_e32 v53, 0xffff0000, v20
	v_lshlrev_b32_e32 v54, 16, v21
	v_and_b32_e32 v55, 0xffff0000, v21
	v_pk_mul_f32 v[10:11], v[50:51], v[50:51]
	v_pk_fma_f32 v[20:21], v[46:47], v[46:47], v[8:9] op_sel_hi:[1,1,0]
	v_pk_fma_f32 v[12:13], v[44:45], v[44:45], v[12:13] op_sel_hi:[1,1,0]
	v_mul_f32_e32 v16, v53, v53
	v_mul_f32_e32 v18, v55, v55
	v_pk_fma_f32 v[10:11], v[48:49], v[48:49], v[10:11]
	v_mov_b32_e32 v38, v12
	v_mov_b32_e32 v8, v20
	v_mul_f32_e32 v22, v41, v41
	v_mul_f32_e32 v23, v42, v42
	v_mul_f32_e32 v40, v43, v43
	v_pk_fma_f32 v[16:17], v[52:53], v[52:53], v[16:17] op_sel_hi:[1,1,0]
	v_pk_fma_f32 v[18:19], v[54:55], v[54:55], v[18:19] op_sel_hi:[1,1,0]
	v_pk_add_f32 v[12:13], v[12:13], v[20:21]
	v_pk_add_f32 v[10:11], v[10:11], v[10:11] op_sel:[0,1] op_sel_hi:[1,0]
	v_pk_mul_f32 v[8:9], v[38:39], v[8:9]
	v_mov_b32_e32 v17, v23
	v_mov_b32_e32 v19, v40
	v_mov_b32_e32 v11, v22
	v_mov_b32_e32 v13, v9
	v_pk_add_f32 v[16:17], v[16:17], v[18:19]
	v_pk_add_f32 v[8:9], v[12:13], v[10:11]
	v_lshl_add_u64 v[10:11], v[2:3], 0, s[0:1]
	v_pk_add_f32 v[8:9], v[8:9], v[16:17]
	v_add_co_u32_e32 v60, vcc, s9, v10
	v_add_f32_e32 v8, v8, v9
	ds_bpermute_b32 v9, v24, v8
	v_addc_co_u32_e32 v61, vcc, 0, v11, vcc
	v_lshl_add_u64 v[58:59], v[10:11], 0, s[2:3]
	s_lshl_b64 s[0:1], s[70:71], 12
	s_waitcnt lgkmcnt(0)
	v_add_f32_e32 v12, v8, v9
	ds_bpermute_b32 v13, v25, v12
	v_lshl_add_u64 v[8:9], v[0:1], 0, s[6:7]
	global_load_dwordx2 v[20:21], v[8:9], off nt
	global_load_dwordx2 v[18:19], v[8:9], off offset:512 nt
	global_load_dwordx2 v[16:17], v[8:9], off offset:1024 nt
	global_load_dwordx2 v[22:23], v[8:9], off offset:1536 nt
	s_cmpk_gt_i32 s4, 0x7fff
	s_waitcnt lgkmcnt(0)
	v_add_f32_e32 v12, v12, v13
	ds_bpermute_b32 v13, v26, v12
	s_waitcnt lgkmcnt(0)
	v_add_f32_e32 v8, v12, v13
	ds_bpermute_b32 v9, v27, v8
	s_waitcnt lgkmcnt(0)
	v_add_f32_e32 v38, v8, v9
	ds_bpermute_b32 v40, v28, v38
	global_load_dwordx2 v[14:15], v[60:61], off nt
	global_load_dwordx2 v[12:13], v[58:59], off offset:512 nt
	global_load_dwordx2 v[10:11], v[58:59], off offset:1024 nt
	global_load_dwordx2 v[8:9], v[58:59], off offset:1536 nt
	v_lshl_add_u64 v[58:59], v[6:7], 0, s[0:1]
	global_load_dwordx2 v[60:61], v[56:57], off offset:1536 nt
	global_load_dwordx2 v[62:63], v[56:57], off offset:1024 nt
	global_load_dwordx2 v[64:65], v[56:57], off offset:512 nt
	v_lshlrev_b32_e32 v56, 16, v36
	s_waitcnt lgkmcnt(0)
	v_add_f32_e32 v38, v38, v40
	ds_bpermute_b32 v40, v29, v38
	v_and_b32_e32 v57, 0xffff0000, v36
	v_lshlrev_b32_e32 v36, 16, v37
	v_and_b32_e32 v37, 0xffff0000, v37
	s_waitcnt lgkmcnt(0)
	v_add_f32_e32 v38, v38, v40
	v_fmamk_f32 v38, v38, 0x3a800000, v30
	v_mul_f32_e32 v40, 0x4f800000, v38
	v_cmp_gt_f32_e32 vcc, s10, v38
	s_nop 1
	v_cndmask_b32_e32 v38, v38, v40, vcc
	v_sqrt_f32_e32 v40, v38
	s_nop 0
	v_add_u32_e32 v66, -1, v40
	v_add_u32_e32 v67, 1, v40
	v_fma_f32 v68, -v66, v40, v38
	v_fma_f32 v69, -v67, v40, v38
	v_cmp_ge_f32_e64 s[0:1], 0, v68
	s_nop 1
	v_cndmask_b32_e64 v40, v40, v66, s[0:1]
	v_cmp_lt_f32_e64 s[0:1], 0, v69
	s_nop 1
	v_cndmask_b32_e64 v40, v40, v67, s[0:1]
	v_mul_f32_e32 v66, 0x37800000, v40
	v_cndmask_b32_e32 v40, v40, v66, vcc
	v_cmp_class_f32_e32 vcc, v38, v31
	s_nop 1
	v_cndmask_b32_e32 v38, v40, v38, vcc
	v_div_scale_f32 v40, s[0:1], v38, v38, 1.0
	v_rcp_f32_e32 v66, v40
	v_div_scale_f32 v67, vcc, 1.0, v38, 1.0
	v_fma_f32 v68, -v40, v66, 1.0
	v_fmac_f32_e32 v66, v68, v66
	v_mul_f32_e32 v68, v67, v66
	v_fma_f32 v69, -v40, v68, v67
	v_fmac_f32_e32 v68, v69, v66
	v_fma_f32 v40, -v40, v68, v67
	v_div_fmas_f32 v40, v40, v66, v68
	v_div_fixup_f32 v38, v40, v38, 1.0
	v_pk_mul_f32 v[44:45], v[38:39], v[44:45] op_sel_hi:[0,1]
	v_pk_mul_f32 v[46:47], v[38:39], v[46:47] op_sel_hi:[0,1]
	s_waitcnt vmcnt(11)
; __global__ void __launch_bounds__(NTHR, 2) hymba_fwd(Params P) {
;     ...
;             for (int u = 0; u < 2; ++u) { const int tr = t0 + u * NGW; if (tr >= NB * SEQ) continue;
;                 float ss = 0.f;
; #pragma unroll
;                 for (int j = 0; j < 4; ++j) ss += (f[u][j].x * f[u][j].x + f[u][j].y * f[u][j].y) + (f[u][j].z * f[u][j].z + f[u][j].w * f[u][j].w);
;                 const float rs = 1.f / sqrtf(wave_sum(ss) * (1.f / 1024.f) + EPS);
;                 f32x4* orow = (f32x4*)(P.out + (size_t)tr * 1024);
; #pragma unroll
;                 for (int j = 0; j < 4; ++j) { const f32x4 gg = *((const f32x4*)P.ffn_post_g + lane + 64 * j); __builtin_nontemporal_store(hv[u][j] + f[u][j] * rs * gg, &orow[lane + 64 * j]); }
	v_pk_fma_f32 v[34:35], v[82:83], v[46:47], v[36:37]
	v_pk_fma_f32 v[32:33], v[80:81], v[44:45], v[56:57]
	global_store_dwordx4 v[58:59], v[32:35], off
	s_nop 1
	v_mov_b32_e32 v46, v49
	v_mov_b32_e32 v47, v51
	v_mov_b32_e32 v49, v50
	v_pk_mul_f32 v[46:47], v[38:39], v[46:47] op_sel_hi:[0,1]
	v_pk_mul_f32 v[48:49], v[38:39], v[48:49] op_sel_hi:[0,1]
	v_mov_b32_e32 v40, v39
	v_pk_mul_f32 v[42:43], v[38:39], v[42:43] op_sel_hi:[0,1]
	s_waitcnt vmcnt(1)
	v_lshlrev_b32_e32 v36, 16, v64
	v_and_b32_e32 v37, 0xffff0000, v64
	v_lshlrev_b32_e32 v44, 16, v65
	v_and_b32_e32 v45, 0xffff0000, v65
	v_pk_fma_f32 v[32:33], v[84:85], v[48:49], v[36:37]
	v_pk_fma_f32 v[34:35], v[86:87], v[46:47], v[44:45]
	global_store_dwordx4 v[58:59], v[32:35], off offset:1024
	s_nop 1
	v_lshlrev_b32_e32 v36, 16, v62
	v_and_b32_e32 v37, 0xffff0000, v62
	v_lshlrev_b32_e32 v44, 16, v63
	v_and_b32_e32 v45, 0xffff0000, v63
	v_pk_mul_f32 v[46:47], v[38:39], v[54:55] op_sel_hi:[0,1]
	v_pk_mul_f32 v[48:49], v[38:39], v[52:53] op_sel_hi:[0,1]
	v_pk_mul_f32 v[38:39], v[38:39], v[40:41] op_sel_hi:[0,1]
	v_pk_fma_f32 v[32:33], v[88:89], v[48:49], v[36:37]
	v_pk_fma_f32 v[34:35], v[90:91], v[46:47], v[44:45]
	global_store_dwordx4 v[58:59], v[32:35], off offset:2048
	s_nop 1
	v_lshlrev_b32_e32 v36, 16, v60
	v_and_b32_e32 v37, 0xffff0000, v60
	v_lshlrev_b32_e32 v44, 16, v61
	v_and_b32_e32 v45, 0xffff0000, v61
	v_pk_fma_f32 v[32:33], v[92:93], v[38:39], v[36:37]
	v_pk_fma_f32 v[34:35], v[94:95], v[42:43], v[44:45]
	global_store_dwordx4 v[58:59], v[32:35], off offset:3072
	s_nop 1
	s_cbranch_scc1 .LBB0_1092
	s_waitcnt vmcnt(4)
	v_lshlrev_b32_e32 v36, 16, v20
	v_and_b32_e32 v37, 0xffff0000, v20
	v_lshlrev_b32_e32 v20, 16, v21
	v_and_b32_e32 v21, 0xffff0000, v21
	v_lshlrev_b32_e32 v33, 16, v22
	v_mul_f32_e32 v32, v21, v21
	v_and_b32_e32 v43, 0xffff0000, v19
	v_and_b32_e32 v42, 0xffff0000, v18
	v_lshlrev_b32_e32 v44, 16, v16
	v_and_b32_e32 v45, 0xffff0000, v16
	v_mul_f32_e32 v16, v37, v37
	v_pk_fma_f32 v[38:39], v[20:21], v[20:21], v[32:33] op_sel_hi:[1,1,0]
	v_lshlrev_b32_e32 v41, 16, v19
	v_lshlrev_b32_e32 v40, 16, v18
	v_pk_mul_f32 v[18:19], v[42:43], v[42:43]
	v_lshlrev_b32_e32 v46, 16, v17
	v_and_b32_e32 v47, 0xffff0000, v17
	v_pk_fma_f32 v[16:17], v[36:37], v[36:37], v[16:17] op_sel_hi:[1,1,0]
	v_and_b32_e32 v35, 0xffff0000, v22
	v_pk_fma_f32 v[18:19], v[40:41], v[40:41], v[18:19]
	v_mov_b32_e32 v32, v16
	v_mov_b32_e32 v48, v38
	v_mov_b32_e32 v49, v33
	v_mul_f32_e32 v34, v35, v35
	v_pk_add_f32 v[16:17], v[16:17], v[38:39]
	v_pk_mul_f32 v[38:39], v[32:33], v[48:49]
	v_pk_add_f32 v[18:19], v[18:19], v[18:19] op_sel:[0,1] op_sel_hi:[1,0]
	v_mov_b32_e32 v17, v39
	v_mov_b32_e32 v19, v34
	v_lshlrev_b32_e32 v22, 16, v23
	v_and_b32_e32 v23, 0xffff0000, v23
	v_pk_add_f32 v[38:39], v[16:17], v[18:19]
	v_mul_f32_e32 v16, v45, v45
	v_mul_f32_e32 v18, v47, v47
	v_mul_f32_e32 v50, v22, v22
	v_mul_f32_e32 v51, v23, v23
	v_pk_fma_f32 v[16:17], v[44:45], v[44:45], v[16:17] op_sel_hi:[1,1,0]
	v_pk_fma_f32 v[18:19], v[46:47], v[46:47], v[18:19] op_sel_hi:[1,1,0]
	v_mov_b32_e32 v17, v50
	v_mov_b32_e32 v19, v51
	v_pk_add_f32 v[48:49], v[16:17], v[18:19]
	v_pk_add_f32 v[38:39], v[38:39], v[48:49]
	s_ashr_i32 s5, s4, 31
	v_add_f32_e32 v32, v38, v39
	ds_bpermute_b32 v34, v24, v32
	v_lshlrev_b32_e32 v38, 16, v14
	s_waitcnt lgkmcnt(0)
	v_add_f32_e32 v32, v32, v34
	ds_bpermute_b32 v34, v25, v32
	s_waitcnt lgkmcnt(0)
	v_add_f32_e32 v32, v32, v34
	ds_bpermute_b32 v34, v26, v32
	s_waitcnt lgkmcnt(0)
	v_add_f32_e32 v32, v32, v34
	ds_bpermute_b32 v34, v27, v32
	s_waitcnt lgkmcnt(0)
	v_add_f32_e32 v32, v32, v34
	ds_bpermute_b32 v34, v28, v32
	s_waitcnt lgkmcnt(0)
	v_add_f32_e32 v32, v32, v34
	ds_bpermute_b32 v34, v29, v32
	s_waitcnt lgkmcnt(0)
	v_add_f32_e32 v32, v32, v34
	v_fmamk_f32 v32, v32, 0x3a800000, v30
	v_mul_f32_e32 v34, 0x4f800000, v32
	v_cmp_gt_f32_e32 vcc, s10, v32
	s_nop 1
	v_cndmask_b32_e32 v32, v32, v34, vcc
	v_sqrt_f32_e32 v34, v32
	s_nop 0
	v_add_u32_e32 v39, -1, v34
	v_fma_f32 v48, -v39, v34, v32
	v_cmp_ge_f32_e64 s[0:1], 0, v48
	v_add_u32_e32 v48, 1, v34
	s_nop 0
	v_cndmask_b32_e64 v39, v34, v39, s[0:1]
	v_fma_f32 v34, -v48, v34, v32
	v_cmp_lt_f32_e64 s[0:1], 0, v34
	s_nop 1
	v_cndmask_b32_e64 v34, v39, v48, s[0:1]
	v_mul_f32_e32 v39, 0x37800000, v34
	v_cndmask_b32_e32 v34, v34, v39, vcc
	v_cmp_class_f32_e32 vcc, v32, v31
	v_and_b32_e32 v39, 0xffff0000, v14
	v_lshlrev_b32_e32 v14, 16, v15
	v_cndmask_b32_e32 v32, v34, v32, vcc
	v_div_scale_f32 v34, s[0:1], v32, v32, 1.0
	v_rcp_f32_e32 v48, v34
	v_and_b32_e32 v15, 0xffff0000, v15
	s_lshl_b64 s[0:1], s[4:5], 12
	v_fma_f32 v49, -v34, v48, 1.0
	v_fmac_f32_e32 v48, v49, v48
	v_div_scale_f32 v49, vcc, 1.0, v32, 1.0
	v_mul_f32_e32 v50, v49, v48
	v_fma_f32 v51, -v34, v50, v49
	v_fmac_f32_e32 v50, v51, v48
	v_fma_f32 v34, -v34, v50, v49
	v_div_fmas_f32 v34, v34, v48, v50
	v_div_fixup_f32 v32, v34, v32, 1.0
	v_pk_mul_f32 v[36:37], v[32:33], v[36:37] op_sel_hi:[0,1]
	v_pk_mul_f32 v[20:21], v[32:33], v[20:21] op_sel_hi:[0,1]
	v_pk_fma_f32 v[18:19], v[82:83], v[20:21], v[14:15]
	v_pk_fma_f32 v[16:17], v[80:81], v[36:37], v[38:39]
	v_lshl_add_u64 v[20:21], v[6:7], 0, s[0:1]
	global_store_dwordx4 v[20:21], v[16:19], off
	s_nop 1
	v_lshlrev_b32_e32 v36, 16, v13
	v_lshlrev_b32_e32 v18, 16, v12
	v_and_b32_e32 v19, 0xffff0000, v12
	v_and_b32_e32 v37, 0xffff0000, v13
	v_mov_b32_e32 v12, v41
	v_mov_b32_e32 v13, v43
	v_mov_b32_e32 v41, v42
	v_pk_mul_f32 v[38:39], v[32:33], v[12:13] op_sel_hi:[0,1]
	v_pk_mul_f32 v[12:13], v[32:33], v[40:41] op_sel_hi:[0,1]
	v_mov_b32_e32 v34, v33
	v_pk_fma_f32 v[12:13], v[84:85], v[12:13], v[18:19]
	v_pk_fma_f32 v[14:15], v[86:87], v[38:39], v[36:37]
	global_store_dwordx4 v[20:21], v[12:15], off offset:1024
	s_nop 1
	v_lshlrev_b32_e32 v16, 16, v10
	v_and_b32_e32 v17, 0xffff0000, v10
	v_lshlrev_b32_e32 v18, 16, v11
	v_and_b32_e32 v19, 0xffff0000, v11
	v_pk_mul_f32 v[36:37], v[32:33], v[46:47] op_sel_hi:[0,1]
	v_pk_mul_f32 v[10:11], v[32:33], v[44:45] op_sel_hi:[0,1]
	v_pk_fma_f32 v[10:11], v[88:89], v[10:11], v[16:17]
	v_pk_fma_f32 v[12:13], v[90:91], v[36:37], v[18:19]
	global_store_dwordx4 v[20:21], v[10:13], off offset:2048
	s_nop 1
	v_lshlrev_b32_e32 v14, 16, v8
	v_and_b32_e32 v15, 0xffff0000, v8
	v_lshlrev_b32_e32 v16, 16, v9
	v_and_b32_e32 v17, 0xffff0000, v9
	v_pk_mul_f32 v[18:19], v[32:33], v[22:23] op_sel_hi:[0,1]
	v_pk_mul_f32 v[8:9], v[32:33], v[34:35] op_sel_hi:[0,1]
	v_pk_fma_f32 v[8:9], v[92:93], v[8:9], v[14:15]
	v_pk_fma_f32 v[10:11], v[94:95], v[18:19], v[16:17]
	global_store_dwordx4 v[20:21], v[8:11], off offset:3072
	s_nop 1
	s_branch .LBB0_1092
